# stack1 plus nt cache policy on the read-once bf16 stream loads of the two row passes (x1 and x2 phases)
# speedup vs baseline: 1.0032x; 1.0032x over previous
; DI unsigned pk2(float a, float b) { f32x2 v = {a, b}; return __builtin_bit_cast(unsigned, __builtin_convertvector(v, bf16x2_t)); }
; DI float bflo(unsigned u) { return __uint_as_float(u << 16); }
; DI float bfhi(unsigned u) { return __uint_as_float(u & 0xffff0000u); }
; DI void x1_phase(const Ptrs& P) {
;     ...
;     for (int row = gw; row < T; row += NGW) {
;         const float rsy = rsqrtf(ssq_y[row] * (1.0f / D) + EPS);
;         const f32x4* xr = (const f32x4*)(P.x + (size_t)row * D) + lane; const u32x2* yr = (const u32x2*)(y + (size_t)row * D) + lane;
;         const f32x4* gp = (const f32x4*)P.g_attn_post + lane; u32x2* op = (u32x2*)((bf16_t*)P.out + (size_t)row * D) + lane;
;         f32x4 v[16]; float s = 0.f;
; #pragma unroll
;         for (int hb = 0; hb < 2; ++hb) {
;             f32x4 a[8], gg[8]; u32x2 yb[8];
; #pragma unroll
;             for (int j = 0; j < 8; ++j) { a[j] = xr[64 * (8 * hb + j)]; gg[j] = gp[64 * (8 * hb + j)]; yb[j] = yr[64 * (8 * hb + j)]; }
; #pragma unroll
;             for (int j = 0; j < 8; ++j) { const f32x4 bq = {bflo(yb[j].x), bfhi(yb[j].x), bflo(yb[j].y), bfhi(yb[j].y)};
;                 const f32x4 r = a[j] + bq * rsy * gg[j]; v[8 * hb + j] = r; u32x2 xb; xb.x = pk2(r[0], r[1]); xb.y = pk2(r[2], r[3]); op[64 * (8 * hb + j)] = xb;
;                 s += (r[0] * r[0] + r[1] * r[1]) + (r[2] * r[2] + r[3] * r[3]); }
.LBB0_636:
	v_add_co_u32_e32 v118, vcc, s17, v106
	global_load_dword v124, v[104:105], off
	s_nop 0
	v_addc_co_u32_e32 v119, vcc, 0, v107, vcc
	v_add_co_u32_e32 v114, vcc, s18, v106
	v_lshl_add_u64 v[116:117], v[108:109], 0, v[50:51]
	s_nop 0
	v_addc_co_u32_e32 v115, vcc, 0, v107, vcc
	v_add_co_u32_e32 v120, vcc, s20, v106
	global_load_dwordx4 v[0:3], v[106:107], off
	global_load_dwordx4 v[4:7], v[52:53], off
	global_load_dwordx4 v[8:11], v[52:53], off offset:1024
	global_load_dwordx4 v[12:15], v[106:107], off offset:1024
	global_load_dwordx4 v[16:19], v[106:107], off offset:2048
	global_load_dwordx4 v[20:23], v[106:107], off offset:3072
	global_load_dwordx4 v[28:31], v[52:53], off offset:2048
	global_load_dwordx4 v[24:27], v[52:53], off offset:3072
	v_addc_co_u32_e32 v121, vcc, 0, v107, vcc
	v_add_co_u32_e32 v126, vcc, s16, v116
	global_load_dwordx4 v[32:35], v[54:55], off
	global_load_dwordx4 v[36:39], v[56:57], off
	global_load_dwordx4 v[40:43], v[58:59], off
	global_load_dwordx4 v[44:47], v[60:61], off
	v_addc_co_u32_e32 v127, vcc, 0, v117, vcc
	v_add_co_u32_e32 v150, vcc, s19, v116
	global_load_dwordx4 v[134:137], v[114:115], off offset:-4096
	global_load_dwordx4 v[138:141], v[118:119], off offset:1024
	global_load_dwordx4 v[142:145], v[118:119], off offset:2048
	global_load_dwordx4 v[146:149], v[118:119], off offset:3072
	v_addc_co_u32_e32 v151, vcc, 0, v117, vcc
	global_load_dwordx2 v[152:153], v[150:151], off offset:-4096 nt
	global_load_dwordx2 v[154:155], v[126:127], off offset:512 nt
	global_load_dwordx2 v[156:157], v[126:127], off offset:1024 nt
	global_load_dwordx2 v[158:159], v[126:127], off offset:1536 nt
	global_load_dwordx2 v[160:161], v[126:127], off offset:2048 nt
	global_load_dwordx2 v[162:163], v[126:127], off offset:2560 nt
	global_load_dwordx2 v[164:165], v[126:127], off offset:3072 nt
	s_nop 0
	global_load_dwordx2 v[126:127], v[126:127], off offset:3584 nt
	v_lshl_add_u64 v[112:113], v[110:111], 0, v[50:51]
	v_add_co_u32_e32 v122, vcc, s17, v112
	v_add_u32_e32 v48, s10, v48
	s_nop 0
	v_addc_co_u32_e32 v123, vcc, 0, v113, vcc
	v_add_co_u32_e32 v118, vcc, s21, v116
	v_lshl_add_u64 v[104:105], v[104:105], 0, s[4:5]
	s_nop 0
	v_addc_co_u32_e32 v119, vcc, 0, v117, vcc
	v_add_co_u32_e32 v116, vcc, s22, v116
	v_lshl_add_u64 v[108:109], v[108:109], 0, s[12:13]
	s_nop 0
	v_addc_co_u32_e32 v117, vcc, 0, v117, vcc
	v_cmp_lt_i32_e32 vcc, s23, v48
	s_or_b64 s[14:15], vcc, s[14:15]
	v_lshl_add_u64 v[110:111], v[110:111], 0, s[12:13]
	v_lshl_add_u64 v[106:107], v[106:107], 0, s[6:7]
	s_waitcnt vmcnt(0)
	v_fmamk_f32 v124, v124, 0x39800000, v49
	v_mul_f32_e32 v125, 0x4b800000, v124
	v_cmp_gt_f32_e32 vcc, s11, v124
	v_lshlrev_b32_e32 v166, 16, v154
	s_nop 0
	v_cndmask_b32_e32 v181, v124, v125, vcc
	v_rsq_f32_e32 v181, v181
	v_lshlrev_b32_e32 v124, 16, v152
	v_and_b32_e32 v125, 0xffff0000, v152
	v_lshlrev_b32_e32 v152, 16, v153
	v_mul_f32_e32 v182, 0x45800000, v181
	v_and_b32_e32 v153, 0xffff0000, v153
	v_and_b32_e32 v167, 0xffff0000, v154
	v_lshlrev_b32_e32 v154, 16, v155
	v_and_b32_e32 v155, 0xffff0000, v155
	v_lshlrev_b32_e32 v168, 16, v156
	v_and_b32_e32 v169, 0xffff0000, v156
	v_lshlrev_b32_e32 v156, 16, v157
	v_and_b32_e32 v157, 0xffff0000, v157
	v_lshlrev_b32_e32 v170, 16, v158
	v_and_b32_e32 v171, 0xffff0000, v158
	v_lshlrev_b32_e32 v158, 16, v159
	v_and_b32_e32 v159, 0xffff0000, v159
	v_lshlrev_b32_e32 v172, 16, v160
	v_and_b32_e32 v173, 0xffff0000, v160
	v_lshlrev_b32_e32 v160, 16, v161
	v_and_b32_e32 v161, 0xffff0000, v161
	v_lshlrev_b32_e32 v174, 16, v162
	v_and_b32_e32 v175, 0xffff0000, v162
	v_lshlrev_b32_e32 v162, 16, v163
	v_and_b32_e32 v163, 0xffff0000, v163
	v_lshlrev_b32_e32 v178, 16, v126
	v_and_b32_e32 v179, 0xffff0000, v126
	v_lshlrev_b32_e32 v126, 16, v127
	v_and_b32_e32 v127, 0xffff0000, v127
	v_cndmask_b32_e32 v182, v181, v182, vcc
	v_lshlrev_b32_e32 v176, 16, v164
	v_and_b32_e32 v177, 0xffff0000, v164
	v_lshlrev_b32_e32 v164, 16, v165
	v_and_b32_e32 v165, 0xffff0000, v165
	v_pk_mul_f32 v[124:125], v[182:183], v[124:125] op_sel_hi:[0,1]
	v_pk_mul_f32 v[152:153], v[182:183], v[152:153] op_sel_hi:[0,1]
	v_pk_mul_f32 v[166:167], v[182:183], v[166:167] op_sel_hi:[0,1]
	v_pk_mul_f32 v[154:155], v[182:183], v[154:155] op_sel_hi:[0,1]
	v_pk_mul_f32 v[168:169], v[182:183], v[168:169] op_sel_hi:[0,1]
	v_pk_mul_f32 v[156:157], v[182:183], v[156:157] op_sel_hi:[0,1]
	v_pk_mul_f32 v[170:171], v[182:183], v[170:171] op_sel_hi:[0,1]
	v_pk_mul_f32 v[158:159], v[182:183], v[158:159] op_sel_hi:[0,1]
	v_pk_mul_f32 v[172:173], v[182:183], v[172:173] op_sel_hi:[0,1]
	v_pk_mul_f32 v[160:161], v[182:183], v[160:161] op_sel_hi:[0,1]
	v_pk_mul_f32 v[174:175], v[182:183], v[174:175] op_sel_hi:[0,1]
	v_pk_mul_f32 v[162:163], v[182:183], v[162:163] op_sel_hi:[0,1]
	v_pk_mul_f32 v[178:179], v[182:183], v[178:179] op_sel_hi:[0,1]
	v_pk_mul_f32 v[184:185], v[182:183], v[126:127] op_sel_hi:[0,1]
	v_pk_mul_f32 v[176:177], v[182:183], v[176:177] op_sel_hi:[0,1]
	v_pk_mul_f32 v[164:165], v[182:183], v[164:165] op_sel_hi:[0,1]
	v_pk_fma_f32 v[2:3], v[6:7], v[152:153], v[2:3]
	v_pk_fma_f32 v[124:125], v[4:5], v[124:125], v[0:1]
	v_pk_fma_f32 v[0:1], v[10:11], v[154:155], v[14:15]
	v_pk_fma_f32 v[126:127], v[8:9], v[166:167], v[12:13]
	v_pk_fma_f32 v[4:5], v[30:31], v[156:157], v[18:19]
	v_pk_fma_f32 v[16:17], v[28:29], v[168:169], v[16:17]
	v_pk_fma_f32 v[6:7], v[26:27], v[158:159], v[22:23]
	v_pk_fma_f32 v[18:19], v[24:25], v[170:171], v[20:21]
	v_pk_fma_f32 v[8:9], v[34:35], v[160:161], v[136:137]
	v_pk_fma_f32 v[20:21], v[32:33], v[172:173], v[134:135]
	v_pk_fma_f32 v[10:11], v[38:39], v[162:163], v[140:141]
	v_pk_fma_f32 v[22:23], v[36:37], v[174:175], v[138:139]
; DI unsigned pk2(float a, float b) { f32x2 v = {a, b}; return __builtin_bit_cast(unsigned, __builtin_convertvector(v, bf16x2_t)); }
; DI float bflo(unsigned u) { return __uint_as_float(u << 16); }
; DI float bfhi(unsigned u) { return __uint_as_float(u & 0xffff0000u); }
; DI void x1_phase(const Ptrs& P) {
;     ...
;         for (int hb = 0; hb < 2; ++hb) {
;             f32x4 a[8], gg[8]; u32x2 yb[8];
; #pragma unroll
;             for (int j = 0; j < 8; ++j) { a[j] = xr[64 * (8 * hb + j)]; gg[j] = gp[64 * (8 * hb + j)]; yb[j] = yr[64 * (8 * hb + j)]; }
; #pragma unroll
;             for (int j = 0; j < 8; ++j) { const f32x4 bq = {bflo(yb[j].x), bfhi(yb[j].x), bflo(yb[j].y), bfhi(yb[j].y)};
;                 const f32x4 r = a[j] + bq * rsy * gg[j]; v[8 * hb + j] = r; u32x2 xb; xb.x = pk2(r[0], r[1]); xb.y = pk2(r[2], r[3]); op[64 * (8 * hb + j)] = xb;
;                 s += (r[0] * r[0] + r[1] * r[1]) + (r[2] * r[2] + r[3] * r[3]); }
;         }
;         const f32x4* g2 = (const f32x4*)P.g_ffn_pre + lane;
;         f32x4 g2v[16];
; #pragma unroll
;         for (int j = 0; j < 16; ++j) g2v[j] = g2[64 * j];
	v_pk_fma_f32 v[14:15], v[46:47], v[184:185], v[148:149]
	v_pk_fma_f32 v[26:27], v[44:45], v[178:179], v[146:147]
	v_pk_fma_f32 v[12:13], v[42:43], v[164:165], v[144:145]
	v_pk_fma_f32 v[24:25], v[40:41], v[176:177], v[142:143]
	v_cvt_pk_bf16_f32 v28, v124, v125
	v_cvt_pk_bf16_f32 v29, v2, v3
	v_cvt_pk_bf16_f32 v34, v126, v127
	v_cvt_pk_bf16_f32 v35, v0, v1
	v_cvt_pk_bf16_f32 v40, v16, v17
	v_cvt_pk_bf16_f32 v41, v4, v5
	v_cvt_pk_bf16_f32 v134, v20, v21
	v_cvt_pk_bf16_f32 v135, v8, v9
	v_cvt_pk_bf16_f32 v140, v22, v23
	v_cvt_pk_bf16_f32 v141, v10, v11
	v_cvt_pk_bf16_f32 v148, v26, v27
	v_cvt_pk_bf16_f32 v149, v14, v15
	v_cvt_pk_bf16_f32 v42, v18, v19
	v_cvt_pk_bf16_f32 v43, v6, v7
	v_cvt_pk_bf16_f32 v142, v24, v25
	v_cvt_pk_bf16_f32 v143, v12, v13
	global_store_dwordx2 v[112:113], v[28:29], off
	global_store_dwordx2 v[112:113], v[34:35], off offset:512
	global_store_dwordx2 v[112:113], v[40:41], off offset:1024
	global_store_dwordx2 v[112:113], v[42:43], off offset:1536
	global_store_dwordx2 v[112:113], v[134:135], off offset:2048
	global_store_dwordx2 v[112:113], v[140:141], off offset:2560
	global_store_dwordx2 v[112:113], v[142:143], off offset:3072
	global_store_dwordx2 v[112:113], v[148:149], off offset:3584
	v_pk_mul_f32 v[30:31], v[2:3], v[2:3]
	v_pk_mul_f32 v[32:33], v[124:125], v[124:125]
	v_pk_mul_f32 v[36:37], v[0:1], v[0:1]
	v_pk_mul_f32 v[38:39], v[126:127], v[126:127]
	v_mul_f32_e32 v45, v6, v6
	v_mul_f32_e32 v47, v7, v7
	v_mul_f32_e32 v44, v17, v17
	v_mul_f32_e32 v46, v5, v5
	v_pk_mul_f32 v[136:137], v[8:9], v[8:9]
	v_pk_mul_f32 v[138:139], v[20:21], v[20:21]
	v_mul_f32_e32 v145, v12, v12
	v_mul_f32_e32 v147, v13, v13
	v_mul_f32_e32 v144, v23, v23
	v_mul_f32_e32 v146, v11, v11
	global_load_dwordx2 v[190:191], v[150:151], off nt
	global_load_dwordx2 v[192:193], v[150:151], off offset:512 nt
	global_load_dwordx2 v[194:195], v[150:151], off offset:1024 nt
	global_load_dwordx2 v[196:197], v[150:151], off offset:1536 nt
	global_load_dwordx2 v[198:199], v[150:151], off offset:2048 nt
	global_load_dwordx2 v[200:201], v[150:151], off offset:2560 nt
	global_load_dwordx2 v[202:203], v[150:151], off offset:3072 nt
	global_load_dwordx2 v[204:205], v[150:151], off offset:3584 nt
	v_pk_mul_f32 v[152:153], v[14:15], v[14:15]
	v_pk_mul_f32 v[174:175], v[26:27], v[26:27]
	v_pk_mov_b32 v[28:29], v[32:33], v[30:31] op_sel:[1,0]
	v_mov_b32_e32 v33, v31
	v_pk_mov_b32 v[30:31], v[38:39], v[36:37] op_sel:[1,0]
	v_mov_b32_e32 v39, v37
	v_pk_fma_f32 v[176:177], v[16:17], v[16:17], v[44:45] op_sel_hi:[1,1,0]
	v_pk_fma_f32 v[178:179], v[4:5], v[4:5], v[46:47] op_sel_hi:[1,1,0]
	v_pk_mov_b32 v[34:35], v[138:139], v[136:137] op_sel:[1,0]
	v_mov_b32_e32 v139, v137
	v_pk_fma_f32 v[184:185], v[22:23], v[22:23], v[144:145] op_sel_hi:[1,1,0]
	v_pk_fma_f32 v[186:187], v[10:11], v[10:11], v[146:147] op_sel_hi:[1,1,0]
	v_pk_mov_b32 v[188:189], v[174:175], v[152:153] op_sel:[1,0]
	v_mov_b32_e32 v175, v153
	v_pk_add_f32 v[206:207], v[28:29], v[32:33]
	v_pk_add_f32 v[208:209], v[30:31], v[38:39]
	v_mov_b32_e32 v177, v45
	v_mov_b32_e32 v179, v47
	v_pk_add_f32 v[210:211], v[34:35], v[138:139]
	v_mov_b32_e32 v185, v145
	v_mov_b32_e32 v187, v147
	global_load_dwordx4 v[28:31], v[62:63], off
	global_load_dwordx4 v[32:35], v[114:115], off
	global_load_dwordx4 v[36:39], v[114:115], off offset:1024
	global_load_dwordx4 v[40:43], v[64:65], off
	global_load_dwordx4 v[44:47], v[66:67], off
	global_load_dwordx4 v[134:137], v[114:115], off offset:2048
	s_nop 0
	global_load_dwordx4 v[112:115], v[114:115], off offset:3072
	s_nop 0
	global_load_dwordx4 v[138:141], v[68:69], off
	global_load_dwordx4 v[142:145], v[70:71], off
	global_load_dwordx4 v[146:149], v[120:121], off
	global_load_dwordx4 v[150:153], v[120:121], off offset:1024
	global_load_dwordx4 v[154:157], v[72:73], off
	global_load_dwordx4 v[158:161], v[74:75], off
	global_load_dwordx4 v[162:165], v[120:121], off offset:2048
	global_load_dwordx4 v[166:169], v[120:121], off offset:3072
	global_load_dwordx4 v[170:173], v[76:77], off
	v_mul_f32_e32 v181, v18, v18
	v_mul_f32_e32 v183, v19, v19
	v_pk_add_f32 v[120:121], v[188:189], v[174:175]
	v_pk_add_f32 v[174:175], v[206:207], v[206:207] op_sel:[0,1] op_sel_hi:[1,0]
	v_pk_add_f32 v[188:189], v[208:209], v[208:209] op_sel:[0,1] op_sel_hi:[1,0]
	v_mov_b32_e32 v175, v181
	v_mov_b32_e32 v189, v183
	v_pk_add_f32 v[176:177], v[176:177], v[178:179]
	v_pk_add_f32 v[184:185], v[184:185], v[186:187]
	v_pk_add_f32 v[186:187], v[120:121], v[120:121] op_sel:[0,1] op_sel_hi:[1,0]
	v_pk_add_f32 v[120:121], v[174:175], v[188:189]
	v_mul_f32_e32 v212, v24, v24
	v_pk_add_f32 v[120:121], v[120:121], v[176:177]
	v_mul_f32_e32 v213, v25, v25
	v_pk_add_f32 v[178:179], v[210:211], v[210:211] op_sel:[0,1] op_sel_hi:[1,0]
	v_pk_add_f32 v[120:121], v[120:121], v[120:121] op_sel:[0,1] op_sel_hi:[1,0]
	v_mov_b32_e32 v179, v213
	v_mov_b32_e32 v121, v212
	v_pk_add_f32 v[120:121], v[120:121], v[178:179]
	s_waitcnt vmcnt(23)
	v_lshlrev_b32_e32 v176, 16, v191
	v_pk_add_f32 v[120:121], v[120:121], v[184:185]
	v_and_b32_e32 v177, 0xffff0000, v191
	v_pk_add_f32 v[174:175], v[120:121], v[120:121] op_sel:[0,1] op_sel_hi:[1,0]
	v_lshlrev_b32_e32 v120, 16, v190
	v_and_b32_e32 v121, 0xffff0000, v190
	s_waitcnt vmcnt(22)
	v_lshlrev_b32_e32 v178, 16, v192
	v_and_b32_e32 v179, 0xffff0000, v192
	v_lshlrev_b32_e32 v184, 16, v193
	v_and_b32_e32 v185, 0xffff0000, v193
	s_waitcnt vmcnt(21)
	v_lshlrev_b32_e32 v188, 16, v194
	v_and_b32_e32 v189, 0xffff0000, v194
	v_lshlrev_b32_e32 v190, 16, v195
	v_and_b32_e32 v191, 0xffff0000, v195
	s_waitcnt vmcnt(20)
; DI unsigned pk2(float a, float b) { f32x2 v = {a, b}; return __builtin_bit_cast(unsigned, __builtin_convertvector(v, bf16x2_t)); }
; DI float bflo(unsigned u) { return __uint_as_float(u << 16); }
; DI float bfhi(unsigned u) { return __uint_as_float(u & 0xffff0000u); }
; DI void x1_phase(const Ptrs& P) {
;     ...
;             for (int j = 0; j < 8; ++j) { a[j] = xr[64 * (8 * hb + j)]; gg[j] = gp[64 * (8 * hb + j)]; yb[j] = yr[64 * (8 * hb + j)]; }
; #pragma unroll
;             for (int j = 0; j < 8; ++j) { const f32x4 bq = {bflo(yb[j].x), bfhi(yb[j].x), bflo(yb[j].y), bfhi(yb[j].y)};
;                 const f32x4 r = a[j] + bq * rsy * gg[j]; v[8 * hb + j] = r; u32x2 xb; xb.x = pk2(r[0], r[1]); xb.y = pk2(r[2], r[3]); op[64 * (8 * hb + j)] = xb;
;                 s += (r[0] * r[0] + r[1] * r[1]) + (r[2] * r[2] + r[3] * r[3]); }
;         }
;         const f32x4* g2 = (const f32x4*)P.g_ffn_pre + lane;
;         f32x4 g2v[16];
; #pragma unroll
;         for (int j = 0; j < 16; ++j) g2v[j] = g2[64 * j];
	v_lshlrev_b32_e32 v192, 16, v196
	v_and_b32_e32 v193, 0xffff0000, v196
	v_lshlrev_b32_e32 v194, 16, v197
	v_and_b32_e32 v195, 0xffff0000, v197
	s_waitcnt vmcnt(18)
	v_lshlrev_b32_e32 v206, 16, v200
	v_and_b32_e32 v207, 0xffff0000, v200
	v_lshlrev_b32_e32 v200, 16, v201
	v_and_b32_e32 v201, 0xffff0000, v201
	s_waitcnt vmcnt(17)
	v_lshlrev_b32_e32 v208, 16, v202
	v_and_b32_e32 v209, 0xffff0000, v202
	v_lshlrev_b32_e32 v202, 16, v203
	v_and_b32_e32 v203, 0xffff0000, v203
	v_lshlrev_b32_e32 v196, 16, v198
	v_and_b32_e32 v197, 0xffff0000, v198
	v_lshlrev_b32_e32 v198, 16, v199
	v_and_b32_e32 v199, 0xffff0000, v199
	s_waitcnt vmcnt(16)
	v_lshlrev_b32_e32 v210, 16, v204
	v_and_b32_e32 v211, 0xffff0000, v204
	v_lshlrev_b32_e32 v204, 16, v205
	v_and_b32_e32 v205, 0xffff0000, v205
	v_pk_mul_f32 v[120:121], v[182:183], v[120:121] op_sel_hi:[0,1]
	v_pk_mul_f32 v[176:177], v[182:183], v[176:177] op_sel_hi:[0,1]
	v_pk_mul_f32 v[178:179], v[182:183], v[178:179] op_sel_hi:[0,1]
	v_pk_mul_f32 v[184:185], v[182:183], v[184:185] op_sel_hi:[0,1]
	v_pk_mul_f32 v[188:189], v[182:183], v[188:189] op_sel_hi:[0,1]
	v_pk_mul_f32 v[190:191], v[182:183], v[190:191] op_sel_hi:[0,1]
	v_pk_mul_f32 v[192:193], v[182:183], v[192:193] op_sel_hi:[0,1]
	v_pk_mul_f32 v[194:195], v[182:183], v[194:195] op_sel_hi:[0,1]
	v_pk_mul_f32 v[206:207], v[182:183], v[206:207] op_sel_hi:[0,1]
	v_pk_mul_f32 v[200:201], v[182:183], v[200:201] op_sel_hi:[0,1]
	v_pk_mul_f32 v[208:209], v[182:183], v[208:209] op_sel_hi:[0,1]
	v_pk_mul_f32 v[202:203], v[182:183], v[202:203] op_sel_hi:[0,1]
	v_pk_mul_f32 v[196:197], v[182:183], v[196:197] op_sel_hi:[0,1]
	v_pk_mul_f32 v[198:199], v[182:183], v[198:199] op_sel_hi:[0,1]
	v_pk_mul_f32 v[210:211], v[182:183], v[210:211] op_sel_hi:[0,1]
	v_pk_mul_f32 v[182:183], v[182:183], v[204:205] op_sel_hi:[0,1]
	s_waitcnt vmcnt(14)
	v_pk_fma_f32 v[176:177], v[30:31], v[176:177], v[34:35]
	v_pk_fma_f32 v[204:205], v[28:29], v[120:121], v[32:33]
	s_waitcnt vmcnt(12)
	v_pk_fma_f32 v[184:185], v[42:43], v[184:185], v[38:39]
	v_pk_fma_f32 v[178:179], v[40:41], v[178:179], v[36:37]
	s_waitcnt vmcnt(10)
	v_pk_fma_f32 v[190:191], v[46:47], v[190:191], v[136:137]
	v_pk_fma_f32 v[188:189], v[44:45], v[188:189], v[134:135]
	s_waitcnt vmcnt(8)
	v_pk_fma_f32 v[194:195], v[140:141], v[194:195], v[114:115]
	v_pk_fma_f32 v[192:193], v[138:139], v[192:193], v[112:113]
	s_waitcnt vmcnt(4)
	v_pk_fma_f32 v[200:201], v[156:157], v[200:201], v[152:153]
	v_pk_fma_f32 v[206:207], v[154:155], v[206:207], v[150:151]
	s_waitcnt vmcnt(2)
	v_pk_fma_f32 v[202:203], v[160:161], v[202:203], v[164:165]
	v_pk_fma_f32 v[208:209], v[158:159], v[208:209], v[162:163]
	v_pk_fma_f32 v[198:199], v[144:145], v[198:199], v[148:149]
	v_pk_fma_f32 v[196:197], v[142:143], v[196:197], v[146:147]
	s_waitcnt vmcnt(0)
	v_pk_fma_f32 v[172:173], v[172:173], v[182:183], v[168:169]
	v_pk_fma_f32 v[170:171], v[170:171], v[210:211], v[166:167]
	v_cvt_pk_bf16_f32 v28, v204, v205
	v_cvt_pk_bf16_f32 v29, v176, v177
	v_cvt_pk_bf16_f32 v30, v178, v179
	v_cvt_pk_bf16_f32 v31, v184, v185
	v_pk_mul_f32 v[34:35], v[190:191], v[190:191]
	v_pk_mul_f32 v[36:37], v[188:189], v[188:189]
	v_cvt_pk_bf16_f32 v38, v192, v193
	v_cvt_pk_bf16_f32 v39, v194, v195
	v_pk_mul_f32 v[44:45], v[200:201], v[200:201]
	v_pk_mul_f32 v[46:47], v[206:207], v[206:207]
	v_cvt_pk_bf16_f32 v112, v208, v209
	v_cvt_pk_bf16_f32 v113, v202, v203
	v_cvt_pk_bf16_f32 v32, v188, v189
	v_cvt_pk_bf16_f32 v33, v190, v191
	v_cvt_pk_bf16_f32 v40, v196, v197
	v_cvt_pk_bf16_f32 v41, v198, v199
	v_cvt_pk_bf16_f32 v42, v206, v207
	v_cvt_pk_bf16_f32 v43, v200, v201
	v_cvt_pk_bf16_f32 v114, v170, v171
	v_cvt_pk_bf16_f32 v115, v172, v173
	v_mul_f32_e32 v120, v205, v205
	v_mul_f32_e32 v134, v177, v177
	v_mul_f32_e32 v136, v193, v193
	v_mul_f32_e32 v138, v195, v195
	v_mul_f32_e32 v140, v209, v209
	v_mul_f32_e32 v142, v203, v203
	global_store_dwordx2 v[122:123], v[28:29], off
	global_store_dwordx2 v[122:123], v[30:31], off offset:512
	global_store_dwordx2 v[122:123], v[32:33], off offset:1024
	v_pk_mov_b32 v[28:29], v[36:37], v[34:35] op_sel:[1,0]
	v_mov_b32_e32 v37, v35
	global_store_dwordx2 v[122:123], v[38:39], off offset:1536
	global_store_dwordx2 v[122:123], v[40:41], off offset:2048
	global_store_dwordx2 v[122:123], v[42:43], off offset:2560
	v_pk_mov_b32 v[30:31], v[46:47], v[44:45] op_sel:[1,0]
	v_mov_b32_e32 v47, v45
	global_store_dwordx2 v[122:123], v[112:113], off offset:3072
	global_store_dwordx2 v[122:123], v[114:115], off offset:3584
	v_pk_fma_f32 v[182:183], v[204:205], v[204:205], v[120:121] op_sel_hi:[1,1,0]
	v_pk_fma_f32 v[210:211], v[176:177], v[176:177], v[134:135] op_sel_hi:[1,1,0]
	v_pk_fma_f32 v[212:213], v[192:193], v[192:193], v[136:137] op_sel_hi:[1,1,0]
	v_pk_fma_f32 v[214:215], v[194:195], v[194:195], v[138:139] op_sel_hi:[1,1,0]
	v_pk_fma_f32 v[216:217], v[208:209], v[208:209], v[140:141] op_sel_hi:[1,1,0]
	v_pk_fma_f32 v[218:219], v[202:203], v[202:203], v[142:143] op_sel_hi:[1,1,0]
	v_pk_add_f32 v[220:221], v[28:29], v[36:37]
	v_pk_add_f32 v[222:223], v[30:31], v[46:47]
	global_load_dwordx4 v[28:31], v[78:79], off
	global_load_dwordx4 v[32:35], v[78:79], off offset:1024
	global_load_dwordx4 v[36:39], v[78:79], off offset:2048
	global_load_dwordx4 v[40:43], v[78:79], off offset:3072
	global_load_dwordx4 v[44:47], v[80:81], off
	global_load_dwordx4 v[112:115], v[82:83], off
	global_load_dwordx4 v[120:123], v[84:85], off
	global_load_dwordx4 v[134:137], v[86:87], off
	global_load_dwordx4 v[138:141], v[88:89], off
	global_load_dwordx4 v[142:145], v[90:91], off
	global_load_dwordx4 v[146:149], v[92:93], off
	global_load_dwordx4 v[150:153], v[94:95], off
; DI unsigned pk2(float a, float b) { f32x2 v = {a, b}; return __builtin_bit_cast(unsigned, __builtin_convertvector(v, bf16x2_t)); }
; DI float wave_sum(float v) {
; #pragma unroll
;     for (int o = 1; o < 64; o <<= 1) v += __shfl_xor(v, o);
;     return v;
; }
; DI void x1_phase(const Ptrs& P) {
;     ...
;                 s += (r[0] * r[0] + r[1] * r[1]) + (r[2] * r[2] + r[3] * r[3]); }
;         }
;         const f32x4* g2 = (const f32x4*)P.g_ffn_pre + lane;
;         f32x4 g2v[16];
; #pragma unroll
;         for (int j = 0; j < 16; ++j) g2v[j] = g2[64 * j];
;         const float rs = rsqrtf(wave_sum(s) * (1.0f / D) + EPS);
;         u32x2* o = (u32x2*)(h2 + (size_t)row * D) + lane;
; #pragma unroll
;         for (int j = 0; j < 16; ++j) { const f32x4 gg = g2v[j]; u32x2 wv; wv.x = pk2(v[j][0] * rs * gg[0], v[j][1] * rs * gg[1]); wv.y = pk2(v[j][2] * rs * gg[2], v[j][3] * rs * gg[3]); o[64 * j] = wv; }
	global_load_dwordx4 v[154:157], v[96:97], off
	global_load_dwordx4 v[158:161], v[98:99], off
	global_load_dwordx4 v[162:165], v[100:101], off
	global_load_dwordx4 v[166:169], v[102:103], off
	v_mul_f32_e32 v181, v184, v184
	v_mul_f32_e32 v224, v185, v185
	v_mul_f32_e32 v175, v178, v178
	v_mul_f32_e32 v187, v179, v179
	v_mov_b32_e32 v183, v181
	v_mov_b32_e32 v211, v224
	v_pk_add_f32 v[174:175], v[174:175], v[186:187]
	v_pk_add_f32 v[182:183], v[182:183], v[210:211]
	v_mul_f32_e32 v225, v196, v196
	v_pk_add_f32 v[174:175], v[174:175], v[182:183]
	v_mul_f32_e32 v226, v197, v197
	v_mul_f32_e32 v227, v198, v198
	v_mul_f32_e32 v228, v199, v199
	v_pk_add_f32 v[210:211], v[220:221], v[220:221] op_sel:[0,1] op_sel_hi:[1,0]
	v_pk_add_f32 v[174:175], v[174:175], v[174:175] op_sel:[0,1] op_sel_hi:[1,0]
	v_mov_b32_e32 v213, v227
	v_mov_b32_e32 v215, v228
	v_mov_b32_e32 v211, v226
	v_mov_b32_e32 v175, v225
	v_pk_add_f32 v[186:187], v[212:213], v[214:215]
	v_pk_add_f32 v[174:175], v[174:175], v[210:211]
	v_mul_f32_e32 v229, v170, v170
	v_pk_add_f32 v[174:175], v[174:175], v[186:187]
	v_mul_f32_e32 v230, v171, v171
	v_mul_f32_e32 v231, v172, v172
	v_mul_f32_e32 v232, v173, v173
	v_pk_add_f32 v[214:215], v[222:223], v[222:223] op_sel:[0,1] op_sel_hi:[1,0]
	v_pk_add_f32 v[174:175], v[174:175], v[174:175] op_sel:[0,1] op_sel_hi:[1,0]
	v_mov_b32_e32 v217, v231
	v_mov_b32_e32 v219, v232
	v_mov_b32_e32 v215, v230
	v_mov_b32_e32 v175, v229
	v_pk_add_f32 v[212:213], v[216:217], v[218:219]
	v_pk_add_f32 v[174:175], v[174:175], v[214:215]
	s_nop 0
	v_pk_add_f32 v[174:175], v[174:175], v[212:213]
	s_nop 0
	v_add_f32_e32 v174, v174, v175
	ds_bpermute_b32 v175, v128, v174
	s_waitcnt lgkmcnt(0)
	v_add_f32_e32 v174, v174, v175
	ds_bpermute_b32 v175, v129, v174
	s_waitcnt lgkmcnt(0)
	v_add_f32_e32 v174, v174, v175
	ds_bpermute_b32 v175, v130, v174
	s_waitcnt lgkmcnt(0)
	v_add_f32_e32 v174, v174, v175
	ds_bpermute_b32 v175, v131, v174
	s_waitcnt lgkmcnt(0)
	v_add_f32_e32 v174, v174, v175
	ds_bpermute_b32 v175, v132, v174
	s_waitcnt lgkmcnt(0)
	v_add_f32_e32 v174, v174, v175
	ds_bpermute_b32 v175, v133, v174
	s_waitcnt lgkmcnt(0)
	v_add_f32_e32 v174, v174, v175
	v_fmamk_f32 v174, v174, 0x39800000, v49
	v_mul_f32_e32 v175, 0x4b800000, v174
	v_cmp_gt_f32_e32 vcc, s11, v174
	s_nop 1
	v_cndmask_b32_e32 v174, v174, v175, vcc
	v_rsq_f32_e32 v174, v174
	s_nop 0
	v_mul_f32_e32 v175, 0x45800000, v174
	v_cndmask_b32_e32 v174, v174, v175, vcc
	v_pk_mul_f32 v[124:125], v[124:125], v[174:175] op_sel_hi:[1,0]
	v_pk_mul_f32 v[2:3], v[2:3], v[174:175] op_sel_hi:[1,0]
	v_pk_mul_f32 v[126:127], v[126:127], v[174:175] op_sel_hi:[1,0]
	v_pk_mul_f32 v[0:1], v[0:1], v[174:175] op_sel_hi:[1,0]
	v_pk_mul_f32 v[16:17], v[16:17], v[174:175] op_sel_hi:[1,0]
	v_pk_mul_f32 v[4:5], v[4:5], v[174:175] op_sel_hi:[1,0]
	v_pk_mul_f32 v[18:19], v[18:19], v[174:175] op_sel_hi:[1,0]
	v_pk_mul_f32 v[6:7], v[6:7], v[174:175] op_sel_hi:[1,0]
	v_pk_mul_f32 v[20:21], v[20:21], v[174:175] op_sel_hi:[1,0]
	v_pk_mul_f32 v[8:9], v[8:9], v[174:175] op_sel_hi:[1,0]
	v_pk_mul_f32 v[22:23], v[22:23], v[174:175] op_sel_hi:[1,0]
	v_pk_mul_f32 v[10:11], v[10:11], v[174:175] op_sel_hi:[1,0]
	v_pk_mul_f32 v[24:25], v[24:25], v[174:175] op_sel_hi:[1,0]
	v_pk_mul_f32 v[12:13], v[12:13], v[174:175] op_sel_hi:[1,0]
	v_pk_mul_f32 v[26:27], v[26:27], v[174:175] op_sel_hi:[1,0]
	v_pk_mul_f32 v[14:15], v[14:15], v[174:175] op_sel_hi:[1,0]
	v_pk_mul_f32 v[182:183], v[204:205], v[174:175] op_sel_hi:[1,0]
	v_pk_mul_f32 v[176:177], v[176:177], v[174:175] op_sel_hi:[1,0]
	v_pk_mul_f32 v[178:179], v[178:179], v[174:175] op_sel_hi:[1,0]
	v_pk_mul_f32 v[184:185], v[184:185], v[174:175] op_sel_hi:[1,0]
	v_pk_mul_f32 v[186:187], v[188:189], v[174:175] op_sel_hi:[1,0]
	v_pk_mul_f32 v[188:189], v[190:191], v[174:175] op_sel_hi:[1,0]
	v_pk_mul_f32 v[190:191], v[192:193], v[174:175] op_sel_hi:[1,0]
	v_pk_mul_f32 v[192:193], v[194:195], v[174:175] op_sel_hi:[1,0]
	v_pk_mul_f32 v[194:195], v[196:197], v[174:175] op_sel_hi:[1,0]
	v_pk_mul_f32 v[196:197], v[198:199], v[174:175] op_sel_hi:[1,0]
	v_pk_mul_f32 v[198:199], v[206:207], v[174:175] op_sel_hi:[1,0]
	v_pk_mul_f32 v[200:201], v[200:201], v[174:175] op_sel_hi:[1,0]
	v_pk_mul_f32 v[204:205], v[208:209], v[174:175] op_sel_hi:[1,0]
	v_pk_mul_f32 v[202:203], v[202:203], v[174:175] op_sel_hi:[1,0]
	v_pk_mul_f32 v[170:171], v[170:171], v[174:175] op_sel_hi:[1,0]
	v_pk_mul_f32 v[172:173], v[172:173], v[174:175] op_sel_hi:[1,0]
	s_waitcnt vmcnt(15)
; DI unsigned pk2(float a, float b) { f32x2 v = {a, b}; return __builtin_bit_cast(unsigned, __builtin_convertvector(v, bf16x2_t)); }
; DI void x1_phase(const Ptrs& P) {
;     ...
;         for (int j = 0; j < 16; ++j) g2v[j] = g2[64 * j];
;         const float rs = rsqrtf(wave_sum(s) * (1.0f / D) + EPS);
;         u32x2* o = (u32x2*)(h2 + (size_t)row * D) + lane;
; #pragma unroll
;         for (int j = 0; j < 16; ++j) { const f32x4 gg = g2v[j]; u32x2 wv; wv.x = pk2(v[j][0] * rs * gg[0], v[j][1] * rs * gg[1]); wv.y = pk2(v[j][2] * rs * gg[2], v[j][3] * rs * gg[3]); o[64 * j] = wv; }
	v_pk_mul_f32 v[28:29], v[28:29], v[124:125]
	v_pk_mul_f32 v[2:3], v[30:31], v[2:3]
	s_waitcnt vmcnt(14)
	v_pk_mul_f32 v[30:31], v[32:33], v[126:127]
	v_pk_mul_f32 v[0:1], v[34:35], v[0:1]
	s_waitcnt vmcnt(13)
	v_pk_mul_f32 v[16:17], v[36:37], v[16:17]
	v_pk_mul_f32 v[4:5], v[38:39], v[4:5]
	s_waitcnt vmcnt(12)
	v_pk_mul_f32 v[18:19], v[40:41], v[18:19]
	v_pk_mul_f32 v[6:7], v[42:43], v[6:7]
	s_waitcnt vmcnt(11)
	v_pk_mul_f32 v[20:21], v[44:45], v[20:21]
	v_pk_mul_f32 v[8:9], v[46:47], v[8:9]
	s_waitcnt vmcnt(10)
	v_pk_mul_f32 v[22:23], v[112:113], v[22:23]
	v_pk_mul_f32 v[10:11], v[114:115], v[10:11]
	s_waitcnt vmcnt(9)
	v_pk_mul_f32 v[24:25], v[120:121], v[24:25]
	v_pk_mul_f32 v[12:13], v[122:123], v[12:13]
	s_waitcnt vmcnt(8)
	v_pk_mul_f32 v[26:27], v[134:135], v[26:27]
	v_pk_mul_f32 v[14:15], v[136:137], v[14:15]
	s_waitcnt vmcnt(7)
	v_pk_mul_f32 v[32:33], v[138:139], v[182:183]
	v_pk_mul_f32 v[34:35], v[140:141], v[176:177]
	s_waitcnt vmcnt(6)
	v_pk_mul_f32 v[36:37], v[142:143], v[178:179]
	v_pk_mul_f32 v[38:39], v[144:145], v[184:185]
	s_waitcnt vmcnt(5)
	v_pk_mul_f32 v[40:41], v[146:147], v[186:187]
	v_pk_mul_f32 v[42:43], v[148:149], v[188:189]
	s_waitcnt vmcnt(4)
	v_pk_mul_f32 v[44:45], v[150:151], v[190:191]
	v_pk_mul_f32 v[46:47], v[152:153], v[192:193]
	s_waitcnt vmcnt(3)
	v_pk_mul_f32 v[112:113], v[154:155], v[194:195]
	v_pk_mul_f32 v[114:115], v[156:157], v[196:197]
	s_waitcnt vmcnt(2)
	v_pk_mul_f32 v[120:121], v[158:159], v[198:199]
	v_pk_mul_f32 v[122:123], v[160:161], v[200:201]
	s_waitcnt vmcnt(1)
	v_pk_mul_f32 v[124:125], v[162:163], v[204:205]
	v_pk_mul_f32 v[126:127], v[164:165], v[202:203]
	s_waitcnt vmcnt(0)
	v_pk_mul_f32 v[134:135], v[166:167], v[170:171]
	v_pk_mul_f32 v[136:137], v[168:169], v[172:173]
	v_cvt_pk_bf16_f32 v28, v28, v29
	v_cvt_pk_bf16_f32 v29, v2, v3
	v_cvt_pk_bf16_f32 v2, v30, v31
	v_cvt_pk_bf16_f32 v3, v0, v1
	v_cvt_pk_bf16_f32 v0, v16, v17
	v_cvt_pk_bf16_f32 v1, v4, v5
	v_cvt_pk_bf16_f32 v4, v18, v19
	v_cvt_pk_bf16_f32 v5, v6, v7
	v_cvt_pk_bf16_f32 v6, v20, v21
	v_cvt_pk_bf16_f32 v7, v8, v9
	v_cvt_pk_bf16_f32 v8, v22, v23
	v_cvt_pk_bf16_f32 v9, v10, v11
	v_cvt_pk_bf16_f32 v10, v24, v25
	v_cvt_pk_bf16_f32 v11, v12, v13
	v_cvt_pk_bf16_f32 v12, v26, v27
	v_cvt_pk_bf16_f32 v13, v14, v15
	v_cvt_pk_bf16_f32 v14, v32, v33
	v_cvt_pk_bf16_f32 v15, v34, v35
	v_cvt_pk_bf16_f32 v16, v36, v37
	v_cvt_pk_bf16_f32 v17, v38, v39
	v_cvt_pk_bf16_f32 v18, v40, v41
	v_cvt_pk_bf16_f32 v19, v42, v43
	v_cvt_pk_bf16_f32 v20, v44, v45
	v_cvt_pk_bf16_f32 v21, v46, v47
	v_cvt_pk_bf16_f32 v22, v112, v113
	v_cvt_pk_bf16_f32 v23, v114, v115
	v_cvt_pk_bf16_f32 v24, v120, v121
	v_cvt_pk_bf16_f32 v25, v122, v123
	v_cvt_pk_bf16_f32 v26, v124, v125
	v_cvt_pk_bf16_f32 v27, v126, v127
	v_cvt_pk_bf16_f32 v30, v134, v135
	v_cvt_pk_bf16_f32 v31, v136, v137
	global_store_dwordx2 v[116:117], v[28:29], off offset:-4096
	global_store_dwordx2 v[118:119], v[2:3], off offset:512
	global_store_dwordx2 v[118:119], v[0:1], off offset:1024
	global_store_dwordx2 v[118:119], v[4:5], off offset:1536
	global_store_dwordx2 v[118:119], v[6:7], off offset:2048
	global_store_dwordx2 v[118:119], v[8:9], off offset:2560
	global_store_dwordx2 v[118:119], v[10:11], off offset:3072
	global_store_dwordx2 v[118:119], v[12:13], off offset:3584
	global_store_dwordx2 v[116:117], v[14:15], off
	global_store_dwordx2 v[116:117], v[16:17], off offset:512
	global_store_dwordx2 v[116:117], v[18:19], off offset:1024
	global_store_dwordx2 v[116:117], v[20:21], off offset:1536
	global_store_dwordx2 v[116:117], v[22:23], off offset:2048
	global_store_dwordx2 v[116:117], v[24:25], off offset:2560
	global_store_dwordx2 v[116:117], v[26:27], off offset:3072
	global_store_dwordx2 v[116:117], v[30:31], off offset:3584
	s_andn2_b64 exec, exec, s[14:15]
	s_cbranch_execnz .LBB0_636

; DI float bflo(unsigned u) { return __uint_as_float(u << 16); }
; DI float bfhi(unsigned u) { return __uint_as_float(u & 0xffff0000u); }
; DI void x2_phase(const Ptrs& P) {
;     ...
;     for (int row = gw; row < T; row += NGW) {
;         const float rsf = rsqrtf(ssq_f[row] * (1.0f / D) + EPS);
;         const u32x2* fr = (const u32x2*)(f + (size_t)row * D) + lane; const f32x4* gp = (const f32x4*)P.g_ffn_post + lane;
;         const u32x2* op = (const u32x2*)((const bf16_t*)P.out + (size_t)row * D) + lane; u32x2* o = (u32x2*)(x2b + (size_t)row * D) + lane;
;         u32x2 abv[16], fbv[16]; f32x4 ggv[16];
; #pragma unroll
;         for (int j = 0; j < 16; ++j) { abv[j] = op[64 * j]; fbv[j] = fr[64 * j]; ggv[j] = gp[64 * j]; }
; #pragma unroll
;         for (int j = 0; j < 16; ++j) { const u32x2 ab = abv[j]; const f32x4 a = {bflo(ab.x), bfhi(ab.x), bflo(ab.y), bfhi(ab.y)}, gg = ggv[j]; const u32x2 fb = fbv[j]; const f32x4 bq = {bflo(fb.x), bfhi(fb.x), bflo(fb.y), bfhi(fb.y)};
;             const f32x4 r = a + bq * rsf * gg;
.LBB0_895:
	global_load_dword v106, v[94:95], off
	v_lshl_add_u64 v[102:103], v[96:97], 0, v[66:67]
	v_add_co_u32_e64 v126, s[4:5], s17, v102
	v_lshl_add_u64 v[100:101], v[98:99], 0, v[66:67]
	s_nop 0
	v_addc_co_u32_e64 v127, s[4:5], 0, v103, s[4:5]
	v_add_co_u32_e32 v118, vcc, s16, v100
	v_add_co_u32_e64 v104, s[4:5], s19, v100
	s_nop 0
	v_addc_co_u32_e32 v119, vcc, 0, v101, vcc
	v_addc_co_u32_e64 v105, s[4:5], 0, v101, s[4:5]
	global_load_dwordx4 v[0:3], v[68:69], off
	global_load_dwordx4 v[4:7], v[68:69], off offset:1024
	global_load_dwordx4 v[8:11], v[68:69], off offset:2048
	global_load_dwordx4 v[12:15], v[68:69], off offset:3072
	global_load_dwordx4 v[16:19], v[70:71], off
	global_load_dwordx4 v[20:23], v[72:73], off
	global_load_dwordx4 v[24:27], v[74:75], off
	global_load_dwordx4 v[28:31], v[76:77], off
	global_load_dwordx4 v[32:35], v[78:79], off
	global_load_dwordx4 v[36:39], v[80:81], off
	global_load_dwordx4 v[40:43], v[82:83], off
	global_load_dwordx4 v[44:47], v[84:85], off
	global_load_dwordx4 v[48:51], v[86:87], off
	global_load_dwordx4 v[52:55], v[88:89], off
	global_load_dwordx4 v[56:59], v[90:91], off
	global_load_dwordx4 v[60:63], v[92:93], off
	global_load_dwordx2 v[108:109], v[102:103], off nt
	global_load_dwordx2 v[110:111], v[102:103], off offset:512 nt
	global_load_dwordx2 v[112:113], v[102:103], off offset:1024 nt
	global_load_dwordx2 v[114:115], v[102:103], off offset:1536 nt
	global_load_dwordx2 v[116:117], v[102:103], off offset:2048 nt
	global_load_dwordx2 v[120:121], v[102:103], off offset:2560 nt
	global_load_dwordx2 v[122:123], v[102:103], off offset:3072 nt
	global_load_dwordx2 v[124:125], v[102:103], off offset:3584 nt
	v_add_co_u32_e64 v102, s[4:5], s20, v100
	v_add_co_u32_e32 v100, vcc, s18, v100
	s_nop 0
	v_addc_co_u32_e64 v103, s[4:5], 0, v101, s[4:5]
	v_addc_co_u32_e32 v101, vcc, 0, v101, vcc
	global_load_dwordx2 v[128:129], v[126:127], off nt
	global_load_dwordx2 v[130:131], v[126:127], off offset:512 nt
	global_load_dwordx2 v[132:133], v[126:127], off offset:1024 nt
	global_load_dwordx2 v[134:135], v[126:127], off offset:1536 nt
	global_load_dwordx2 v[136:137], v[126:127], off offset:2048 nt
	global_load_dwordx2 v[138:139], v[126:127], off offset:2560 nt
	global_load_dwordx2 v[140:141], v[126:127], off offset:3072 nt
	s_nop 0
	global_load_dwordx2 v[126:127], v[126:127], off offset:3584 nt
	s_nop 0
	global_load_dwordx2 v[142:143], v[118:119], off offset:512 nt
	global_load_dwordx2 v[144:145], v[118:119], off offset:1024 nt
	global_load_dwordx2 v[146:147], v[118:119], off offset:1536 nt
	global_load_dwordx2 v[148:149], v[118:119], off offset:2048 nt
	global_load_dwordx2 v[150:151], v[118:119], off offset:2560 nt
	global_load_dwordx2 v[152:153], v[118:119], off offset:3072 nt
	s_nop 0
	global_load_dwordx2 v[118:119], v[118:119], off offset:3584 nt
	s_nop 0
	global_load_dwordx2 v[154:155], v[100:101], off offset:-4096 nt
	global_load_dwordx2 v[156:157], v[100:101], off nt
	global_load_dwordx2 v[158:159], v[100:101], off offset:512 nt
	global_load_dwordx2 v[160:161], v[100:101], off offset:1024 nt
	global_load_dwordx2 v[162:163], v[100:101], off offset:1536 nt
	global_load_dwordx2 v[164:165], v[100:101], off offset:2048 nt
	global_load_dwordx2 v[166:167], v[100:101], off offset:2560 nt
	global_load_dwordx2 v[168:169], v[100:101], off offset:3072 nt
	s_nop 0
	global_load_dwordx2 v[100:101], v[100:101], off offset:3584 nt
	v_add_u32_e32 v64, s8, v64
	v_cmp_lt_i32_e64 s[4:5], s21, v64
	v_lshl_add_u64 v[94:95], v[94:95], 0, s[10:11]
	v_lshl_add_u64 v[96:97], v[96:97], 0, s[12:13]
	v_lshl_add_u64 v[98:99], v[98:99], 0, s[12:13]
	s_or_b64 s[14:15], s[4:5], s[14:15]
	s_waitcnt vmcnt(0)
	v_fmamk_f32 v181, v106, 0x39800000, v65
	v_mul_f32_e32 v186, 0x4b800000, v181
	v_cmp_gt_f32_e32 vcc, s9, v181
	v_lshlrev_b32_e32 v106, 16, v108
	s_nop 0
	v_cndmask_b32_e32 v181, v181, v186, vcc
	v_rsq_f32_e32 v181, v181
	v_and_b32_e32 v107, 0xffff0000, v108
	v_lshlrev_b32_e32 v108, 16, v109
	v_and_b32_e32 v109, 0xffff0000, v109
	v_mul_f32_e32 v234, 0x45800000, v181
	v_cndmask_b32_e32 v234, v181, v234, vcc
	v_lshlrev_b32_e32 v202, 16, v142
	v_lshlrev_b32_e32 v216, 16, v154
	v_and_b32_e32 v217, 0xffff0000, v154
	v_lshlrev_b32_e32 v154, 16, v155
	v_and_b32_e32 v155, 0xffff0000, v155
	v_and_b32_e32 v203, 0xffff0000, v142
	v_lshlrev_b32_e32 v142, 16, v143
	v_and_b32_e32 v143, 0xffff0000, v143
	v_lshlrev_b32_e32 v204, 16, v144
	v_and_b32_e32 v205, 0xffff0000, v144
	v_lshlrev_b32_e32 v144, 16, v145
	v_and_b32_e32 v145, 0xffff0000, v145
	v_lshlrev_b32_e32 v206, 16, v146
	v_and_b32_e32 v207, 0xffff0000, v146
	v_lshlrev_b32_e32 v146, 16, v147
	v_and_b32_e32 v147, 0xffff0000, v147
	v_lshlrev_b32_e32 v208, 16, v148
	v_and_b32_e32 v209, 0xffff0000, v148
	v_lshlrev_b32_e32 v148, 16, v149
	v_and_b32_e32 v149, 0xffff0000, v149
	v_lshlrev_b32_e32 v210, 16, v150
	v_and_b32_e32 v211, 0xffff0000, v150
	v_lshlrev_b32_e32 v150, 16, v151
	v_and_b32_e32 v151, 0xffff0000, v151
	v_lshlrev_b32_e32 v212, 16, v152
	v_and_b32_e32 v213, 0xffff0000, v152
	v_lshlrev_b32_e32 v152, 16, v153
	v_and_b32_e32 v153, 0xffff0000, v153
	v_lshlrev_b32_e32 v214, 16, v118
	v_and_b32_e32 v215, 0xffff0000, v118
	v_lshlrev_b32_e32 v118, 16, v119
	v_and_b32_e32 v119, 0xffff0000, v119
	v_lshlrev_b32_e32 v218, 16, v156
	v_and_b32_e32 v219, 0xffff0000, v156
	v_lshlrev_b32_e32 v156, 16, v157
	v_and_b32_e32 v157, 0xffff0000, v157
	v_lshlrev_b32_e32 v220, 16, v158
	v_and_b32_e32 v221, 0xffff0000, v158
	v_lshlrev_b32_e32 v158, 16, v159
	v_and_b32_e32 v159, 0xffff0000, v159
	v_lshlrev_b32_e32 v222, 16, v160
	v_and_b32_e32 v223, 0xffff0000, v160
	v_lshlrev_b32_e32 v160, 16, v161
; DI float bflo(unsigned u) { return __uint_as_float(u << 16); }
; DI float bfhi(unsigned u) { return __uint_as_float(u & 0xffff0000u); }
; DI void x2_phase(const Ptrs& P) {
;     ...
;         for (int j = 0; j < 16; ++j) { const u32x2 ab = abv[j]; const f32x4 a = {bflo(ab.x), bfhi(ab.x), bflo(ab.y), bfhi(ab.y)}, gg = ggv[j]; const u32x2 fb = fbv[j]; const f32x4 bq = {bflo(fb.x), bfhi(fb.x), bflo(fb.y), bfhi(fb.y)};
;             const f32x4 r = a + bq * rsf * gg;
	v_and_b32_e32 v161, 0xffff0000, v161
	v_lshlrev_b32_e32 v224, 16, v162
	v_and_b32_e32 v225, 0xffff0000, v162
	v_lshlrev_b32_e32 v162, 16, v163
	v_and_b32_e32 v163, 0xffff0000, v163
	v_lshlrev_b32_e32 v226, 16, v164
	v_and_b32_e32 v227, 0xffff0000, v164
	v_lshlrev_b32_e32 v164, 16, v165
	v_and_b32_e32 v165, 0xffff0000, v165
	v_lshlrev_b32_e32 v228, 16, v166
	v_and_b32_e32 v229, 0xffff0000, v166
	v_lshlrev_b32_e32 v166, 16, v167
	v_and_b32_e32 v167, 0xffff0000, v167
	v_lshlrev_b32_e32 v230, 16, v168
	v_and_b32_e32 v231, 0xffff0000, v168
	v_lshlrev_b32_e32 v168, 16, v169
	v_and_b32_e32 v169, 0xffff0000, v169
	v_lshlrev_b32_e32 v232, 16, v100
	v_and_b32_e32 v233, 0xffff0000, v100
	v_lshlrev_b32_e32 v100, 16, v101
	v_and_b32_e32 v101, 0xffff0000, v101
	v_pk_mul_f32 v[216:217], v[234:235], v[216:217] op_sel_hi:[0,1]
	v_pk_mul_f32 v[154:155], v[234:235], v[154:155] op_sel_hi:[0,1]
	v_lshlrev_b32_e32 v170, 16, v110
	v_and_b32_e32 v171, 0xffff0000, v110
	v_lshlrev_b32_e32 v110, 16, v111
	v_and_b32_e32 v111, 0xffff0000, v111
	v_lshlrev_b32_e32 v172, 16, v112
	v_and_b32_e32 v173, 0xffff0000, v112
	v_lshlrev_b32_e32 v112, 16, v113
	v_and_b32_e32 v113, 0xffff0000, v113
	v_lshlrev_b32_e32 v174, 16, v114
	v_and_b32_e32 v175, 0xffff0000, v114
	v_lshlrev_b32_e32 v114, 16, v115
	v_and_b32_e32 v115, 0xffff0000, v115
	v_lshlrev_b32_e32 v176, 16, v116
	v_and_b32_e32 v177, 0xffff0000, v116
	v_lshlrev_b32_e32 v116, 16, v117
	v_and_b32_e32 v117, 0xffff0000, v117
	v_lshlrev_b32_e32 v178, 16, v120
	v_and_b32_e32 v179, 0xffff0000, v120
	v_lshlrev_b32_e32 v120, 16, v121
	v_and_b32_e32 v121, 0xffff0000, v121
	v_lshlrev_b32_e32 v182, 16, v122
	v_and_b32_e32 v183, 0xffff0000, v122
	v_lshlrev_b32_e32 v122, 16, v123
	v_and_b32_e32 v123, 0xffff0000, v123
	v_lshlrev_b32_e32 v184, 16, v124
	v_and_b32_e32 v185, 0xffff0000, v124
	v_lshlrev_b32_e32 v124, 16, v125
	v_and_b32_e32 v125, 0xffff0000, v125
	v_lshlrev_b32_e32 v186, 16, v128
	v_and_b32_e32 v187, 0xffff0000, v128
	v_lshlrev_b32_e32 v128, 16, v129
	v_and_b32_e32 v129, 0xffff0000, v129
	v_lshlrev_b32_e32 v188, 16, v130
	v_and_b32_e32 v189, 0xffff0000, v130
	v_lshlrev_b32_e32 v130, 16, v131
	v_and_b32_e32 v131, 0xffff0000, v131
	v_lshlrev_b32_e32 v190, 16, v132
	v_and_b32_e32 v191, 0xffff0000, v132
	v_lshlrev_b32_e32 v132, 16, v133
	v_and_b32_e32 v133, 0xffff0000, v133
	v_lshlrev_b32_e32 v192, 16, v134
	v_and_b32_e32 v193, 0xffff0000, v134
	v_lshlrev_b32_e32 v134, 16, v135
	v_and_b32_e32 v135, 0xffff0000, v135
	v_lshlrev_b32_e32 v194, 16, v136
	v_and_b32_e32 v195, 0xffff0000, v136
	v_lshlrev_b32_e32 v136, 16, v137
	v_and_b32_e32 v137, 0xffff0000, v137
	v_lshlrev_b32_e32 v196, 16, v138
	v_and_b32_e32 v197, 0xffff0000, v138
	v_lshlrev_b32_e32 v138, 16, v139
	v_and_b32_e32 v139, 0xffff0000, v139
	v_lshlrev_b32_e32 v198, 16, v140
	v_and_b32_e32 v199, 0xffff0000, v140
	v_lshlrev_b32_e32 v140, 16, v141
	v_and_b32_e32 v141, 0xffff0000, v141
	v_lshlrev_b32_e32 v200, 16, v126
	v_and_b32_e32 v201, 0xffff0000, v126
	v_lshlrev_b32_e32 v126, 16, v127
	v_and_b32_e32 v127, 0xffff0000, v127
	v_pk_mul_f32 v[202:203], v[234:235], v[202:203] op_sel_hi:[0,1]
	v_pk_mul_f32 v[142:143], v[234:235], v[142:143] op_sel_hi:[0,1]
	v_pk_mul_f32 v[204:205], v[234:235], v[204:205] op_sel_hi:[0,1]
	v_pk_mul_f32 v[144:145], v[234:235], v[144:145] op_sel_hi:[0,1]
	v_pk_mul_f32 v[206:207], v[234:235], v[206:207] op_sel_hi:[0,1]
	v_pk_mul_f32 v[146:147], v[234:235], v[146:147] op_sel_hi:[0,1]
	v_pk_mul_f32 v[208:209], v[234:235], v[208:209] op_sel_hi:[0,1]
	v_pk_mul_f32 v[148:149], v[234:235], v[148:149] op_sel_hi:[0,1]
	v_pk_mul_f32 v[210:211], v[234:235], v[210:211] op_sel_hi:[0,1]
	v_pk_mul_f32 v[150:151], v[234:235], v[150:151] op_sel_hi:[0,1]
	v_pk_mul_f32 v[212:213], v[234:235], v[212:213] op_sel_hi:[0,1]
	v_pk_mul_f32 v[152:153], v[234:235], v[152:153] op_sel_hi:[0,1]
	v_pk_mul_f32 v[214:215], v[234:235], v[214:215] op_sel_hi:[0,1]
	v_pk_mul_f32 v[118:119], v[234:235], v[118:119] op_sel_hi:[0,1]
	v_pk_mul_f32 v[218:219], v[234:235], v[218:219] op_sel_hi:[0,1]
	v_pk_mul_f32 v[156:157], v[234:235], v[156:157] op_sel_hi:[0,1]
	v_pk_mul_f32 v[220:221], v[234:235], v[220:221] op_sel_hi:[0,1]
	v_pk_mul_f32 v[158:159], v[234:235], v[158:159] op_sel_hi:[0,1]
	v_pk_mul_f32 v[222:223], v[234:235], v[222:223] op_sel_hi:[0,1]
	v_pk_mul_f32 v[160:161], v[234:235], v[160:161] op_sel_hi:[0,1]
	v_pk_mul_f32 v[224:225], v[234:235], v[224:225] op_sel_hi:[0,1]
; DI unsigned pk2(float a, float b) { f32x2 v = {a, b}; return __builtin_bit_cast(unsigned, __builtin_convertvector(v, bf16x2_t)); }
; DI float bflo(unsigned u) { return __uint_as_float(u << 16); }
; DI float bfhi(unsigned u) { return __uint_as_float(u & 0xffff0000u); }
; DI void x2_phase(const Ptrs& P) {
;     ...
;         for (int j = 0; j < 16; ++j) { const u32x2 ab = abv[j]; const f32x4 a = {bflo(ab.x), bfhi(ab.x), bflo(ab.y), bfhi(ab.y)}, gg = ggv[j]; const u32x2 fb = fbv[j]; const f32x4 bq = {bflo(fb.x), bfhi(fb.x), bflo(fb.y), bfhi(fb.y)};
;             const f32x4 r = a + bq * rsf * gg;
;             u32x2 wv; wv.x = pk2(r[0], r[1]); wv.y = pk2(r[2], r[3]); o[64 * j] = wv; }
	v_pk_mul_f32 v[162:163], v[234:235], v[162:163] op_sel_hi:[0,1]
	v_pk_mul_f32 v[226:227], v[234:235], v[226:227] op_sel_hi:[0,1]
	v_pk_mul_f32 v[164:165], v[234:235], v[164:165] op_sel_hi:[0,1]
	v_pk_mul_f32 v[228:229], v[234:235], v[228:229] op_sel_hi:[0,1]
	v_pk_mul_f32 v[166:167], v[234:235], v[166:167] op_sel_hi:[0,1]
	v_pk_mul_f32 v[230:231], v[234:235], v[230:231] op_sel_hi:[0,1]
	v_pk_mul_f32 v[168:169], v[234:235], v[168:169] op_sel_hi:[0,1]
	v_pk_mul_f32 v[232:233], v[234:235], v[232:233] op_sel_hi:[0,1]
	v_pk_mul_f32 v[100:101], v[234:235], v[100:101] op_sel_hi:[0,1]
	v_pk_fma_f32 v[2:3], v[2:3], v[154:155], v[108:109]
	v_pk_fma_f32 v[0:1], v[0:1], v[216:217], v[106:107]
	v_pk_fma_f32 v[6:7], v[6:7], v[142:143], v[110:111]
	v_pk_fma_f32 v[4:5], v[4:5], v[202:203], v[170:171]
	v_pk_fma_f32 v[10:11], v[10:11], v[144:145], v[112:113]
	v_pk_fma_f32 v[8:9], v[8:9], v[204:205], v[172:173]
	v_pk_fma_f32 v[14:15], v[14:15], v[146:147], v[114:115]
	v_pk_fma_f32 v[12:13], v[12:13], v[206:207], v[174:175]
	v_pk_fma_f32 v[18:19], v[18:19], v[148:149], v[116:117]
	v_pk_fma_f32 v[16:17], v[16:17], v[208:209], v[176:177]
	v_pk_fma_f32 v[22:23], v[22:23], v[150:151], v[120:121]
	v_pk_fma_f32 v[20:21], v[20:21], v[210:211], v[178:179]
	v_pk_fma_f32 v[26:27], v[26:27], v[152:153], v[122:123]
	v_pk_fma_f32 v[24:25], v[24:25], v[212:213], v[182:183]
	v_pk_fma_f32 v[30:31], v[30:31], v[118:119], v[124:125]
	v_pk_fma_f32 v[28:29], v[28:29], v[214:215], v[184:185]
	v_pk_fma_f32 v[34:35], v[34:35], v[156:157], v[128:129]
	v_pk_fma_f32 v[32:33], v[32:33], v[218:219], v[186:187]
	v_pk_fma_f32 v[38:39], v[38:39], v[158:159], v[130:131]
	v_pk_fma_f32 v[36:37], v[36:37], v[220:221], v[188:189]
	v_pk_fma_f32 v[42:43], v[42:43], v[160:161], v[132:133]
	v_pk_fma_f32 v[40:41], v[40:41], v[222:223], v[190:191]
	v_pk_fma_f32 v[46:47], v[46:47], v[162:163], v[134:135]
	v_pk_fma_f32 v[44:45], v[44:45], v[224:225], v[192:193]
	v_pk_fma_f32 v[50:51], v[50:51], v[164:165], v[136:137]
	v_pk_fma_f32 v[48:49], v[48:49], v[226:227], v[194:195]
	v_pk_fma_f32 v[54:55], v[54:55], v[166:167], v[138:139]
	v_pk_fma_f32 v[52:53], v[52:53], v[228:229], v[196:197]
	v_pk_fma_f32 v[58:59], v[58:59], v[168:169], v[140:141]
	v_pk_fma_f32 v[56:57], v[56:57], v[230:231], v[198:199]
	v_pk_fma_f32 v[62:63], v[62:63], v[100:101], v[126:127]
	v_pk_fma_f32 v[60:61], v[60:61], v[232:233], v[200:201]
	v_cvt_pk_bf16_f32 v0, v0, v1
	v_cvt_pk_bf16_f32 v1, v2, v3
	v_cvt_pk_bf16_f32 v2, v4, v5
	v_cvt_pk_bf16_f32 v3, v6, v7
	v_cvt_pk_bf16_f32 v4, v8, v9
	v_cvt_pk_bf16_f32 v5, v10, v11
	v_cvt_pk_bf16_f32 v6, v12, v13
	v_cvt_pk_bf16_f32 v7, v14, v15
	v_cvt_pk_bf16_f32 v8, v16, v17
	v_cvt_pk_bf16_f32 v9, v18, v19
	v_cvt_pk_bf16_f32 v10, v20, v21
	v_cvt_pk_bf16_f32 v11, v22, v23
	v_cvt_pk_bf16_f32 v12, v24, v25
	v_cvt_pk_bf16_f32 v13, v26, v27
	v_cvt_pk_bf16_f32 v14, v28, v29
	v_cvt_pk_bf16_f32 v15, v30, v31
	v_cvt_pk_bf16_f32 v16, v32, v33
	v_cvt_pk_bf16_f32 v17, v34, v35
	v_cvt_pk_bf16_f32 v18, v36, v37
	v_cvt_pk_bf16_f32 v19, v38, v39
	v_cvt_pk_bf16_f32 v20, v40, v41
	v_cvt_pk_bf16_f32 v21, v42, v43
	v_cvt_pk_bf16_f32 v22, v44, v45
	v_cvt_pk_bf16_f32 v23, v46, v47
	v_cvt_pk_bf16_f32 v24, v48, v49
	v_cvt_pk_bf16_f32 v25, v50, v51
	v_cvt_pk_bf16_f32 v26, v52, v53
	v_cvt_pk_bf16_f32 v27, v54, v55
	v_cvt_pk_bf16_f32 v28, v56, v57
	v_cvt_pk_bf16_f32 v29, v58, v59
	v_cvt_pk_bf16_f32 v30, v60, v61
	v_cvt_pk_bf16_f32 v31, v62, v63
	global_store_dwordx2 v[102:103], v[0:1], off offset:-4096
	global_store_dwordx2 v[104:105], v[2:3], off offset:512
	global_store_dwordx2 v[104:105], v[4:5], off offset:1024
	global_store_dwordx2 v[104:105], v[6:7], off offset:1536
	global_store_dwordx2 v[104:105], v[8:9], off offset:2048
	global_store_dwordx2 v[104:105], v[10:11], off offset:2560
	global_store_dwordx2 v[104:105], v[12:13], off offset:3072
	global_store_dwordx2 v[104:105], v[14:15], off offset:3584
	global_store_dwordx2 v[102:103], v[16:17], off
	global_store_dwordx2 v[102:103], v[18:19], off offset:512
	global_store_dwordx2 v[102:103], v[20:21], off offset:1024
	global_store_dwordx2 v[102:103], v[22:23], off offset:1536
	global_store_dwordx2 v[102:103], v[24:25], off offset:2048
	global_store_dwordx2 v[102:103], v[26:27], off offset:2560
	global_store_dwordx2 v[102:103], v[28:29], off offset:3072
	global_store_dwordx2 v[102:103], v[30:31], off offset:3584
	s_andn2_b64 exec, exec, s[14:15]
	s_cbranch_execnz .LBB0_895
